# prompt MLA attention: K tile via LDS-DMA (global_load_lds_dwordx4, padded-row layout through per-lane source offsets) into the other LDS set one tile ahead; register-staged K loads + masked ds_write_b
# speedup vs baseline: 1.0082x; 1.0001x over previous
.LBB0_546:
	s_or_b64 exec, exec, s[6:7]
	s_mul_i32 s6, s57, 0x140000
	s_mov_b32 s8, 0x66666667
	s_add_u32 s22, s43, s6
	s_movk_i32 s6, 0x500
	v_mul_hi_i32 v0, v6, s8
	s_addc_u32 s23, s44, 0
	v_cmp_gt_i32_e64 s[6:7], s6, v6
	v_lshrrev_b32_e32 v3, 31, v0
	v_ashrrev_i32_e32 v7, 3, v0
	s_and_saveexec_b64 s[8:9], s[6:7]
	s_cbranch_execz .LBB0_548
	v_add_u32_e32 v0, v7, v3
	v_mul_lo_u32 v4, v0, 20
	v_sub_u32_e32 v8, v6, v4
	v_mov_b64_e32 v[4:5], s[22:23]
	s_movk_i32 s10, 0x140
	v_lshlrev_b32_e32 v8, 3, v8
	v_mad_i64_i32 v[4:5], s[10:11], v0, s10, v[4:5]
	v_ashrrev_i32_e32 v9, 31, v8
	v_lshl_add_u64 v[4:5], v[8:9], 1, v[4:5]
.LBB0_548:
	s_or_b64 exec, exec, s[8:9]
	v_add_u32_e32 v8, 0x200, v6
	s_mov_b32 s10, 0x66666667
	s_movk_i32 s8, 0x300
	v_mul_hi_i32 v0, v8, s10
	v_cmp_gt_i32_e64 s[8:9], s8, v6
	v_lshrrev_b32_e32 v9, 31, v0
	v_ashrrev_i32_e32 v10, 3, v0
	s_and_saveexec_b64 s[10:11], s[8:9]
	s_cbranch_execz .LBB0_550
	v_add_u32_e32 v0, v10, v9
	v_mul_lo_u32 v4, v0, 20
	v_sub_u32_e32 v11, v8, v4
	v_mov_b64_e32 v[4:5], s[22:23]
	s_movk_i32 s12, 0x140
	v_lshlrev_b32_e32 v12, 3, v11
	v_mad_i64_i32 v[4:5], s[12:13], v0, s12, v[4:5]
	v_ashrrev_i32_e32 v13, 31, v12
	v_lshl_add_u64 v[4:5], v[12:13], 1, v[4:5]
.LBB0_550:
	s_or_b64 exec, exec, s[10:11]
	s_movk_i32 s10, 0x100
	s_movk_i32 s12, 0xff
	v_add_u32_e32 v0, 0x400, v6
	v_cmp_gt_i32_e64 s[10:11], s10, v6
	v_cmp_lt_i32_e64 s[12:13], s12, v6
	s_and_saveexec_b64 s[58:59], s[12:13]
	s_xor_b64 s[12:13], exec, s[58:59]
	s_mov_b32 s58, 0xcccccccd
	v_mul_hi_u32 v4, v0, s58
	v_lshrrev_b32_e32 v185, 4, v4
	v_mul_lo_u32 v4, v185, 20
	v_sub_u32_e32 v11, v0, v4
	v_lshlrev_b32_e32 v0, 3, v11
	v_mov_b64_e32 v[4:5], v[0:1]
	s_or_saveexec_b64 s[12:13], s[12:13]
	s_xor_b64 exec, exec, s[12:13]
	s_cbranch_execz .LBB0_554
	s_mov_b32 s58, 0x66666667
	v_mul_hi_i32 v4, v0, s58
	v_lshrrev_b32_e32 v5, 31, v4
	v_ashrrev_i32_e32 v4, 3, v4
	v_add_u32_e32 v185, v4, v5
	v_mul_lo_u32 v4, v185, 20
	v_sub_u32_e32 v11, v0, v4
	v_mov_b64_e32 v[4:5], s[22:23]
	s_movk_i32 s58, 0x140
	v_mad_i64_i32 v[12:13], s[58:59], v185, s58, v[4:5]
	v_lshlrev_b32_e32 v4, 3, v11
	v_ashrrev_i32_e32 v5, 31, v4
	v_lshl_add_u64 v[12:13], v[4:5], 1, v[12:13]
.LBB0_554:
	s_or_b64 exec, exec, s[12:13]
	s_lshl_b32 s12, s57, 20
	v_ashrrev_i32_e32 v16, 3, v8
	s_add_u32 s12, s45, s12
	v_ashrrev_i32_e32 v12, 3, v6
	v_ashrrev_i32_e32 v17, 31, v16
	s_addc_u32 s13, s46, 0
	v_ashrrev_i32_e32 v13, 31, v12
	v_lshlrev_b64 v[18:19], 13, v[16:17]
	v_lshlrev_b32_e32 v0, 4, v6
	v_lshlrev_b64 v[14:15], 13, v[12:13]
	v_lshl_add_u64 v[18:19], s[12:13], 0, v[18:19]
	v_and_b32_e32 v0, 0x70, v0
	v_lshl_add_u64 v[14:15], s[12:13], 0, v[14:15]
	v_lshl_add_u64 v[174:175], v[18:19], 0, v[0:1]
	v_lshl_add_u64 v[172:173], v[14:15], 0, v[0:1]
	global_load_dwordx4 v[164:167], v[174:175], off
	global_load_dwordx4 v[168:171], v[172:173], off
	v_add_u32_e32 v186, v7, v3
	v_add_u32_e32 v17, 0, v0
	v_mul_lo_u32 v0, v186, 20
	s_movk_i32 s12, 0x150
	v_add_u32_e32 v187, v10, v9
	v_and_b32_e32 v13, 31, v6
	v_sub_u32_e32 v0, v6, v0
	v_mul_lo_u32 v6, v187, s12
	v_mul_lo_u32 v3, v186, s12
	v_add_u32_e32 v20, 0, v6
	v_mul_lo_u32 v6, v185, s12
	s_movk_i32 s12, 0x88
	v_add_u32_e32 v18, 0, v3
	v_mul_lo_u32 v3, v187, 20
	v_add_u32_e32 v22, 0, v6
	v_mul_lo_u32 v24, v12, s12
	v_mul_lo_u32 v16, v16, s12
	v_lshlrev_b32_e32 v6, 3, v0
	v_readlane_b32 s12, v253, 29
	v_sub_u32_e32 v3, v8, v3
	v_ashrrev_i32_e32 v7, 31, v6
	v_readlane_b32 s13, v253, 30
	s_mov_b32 s12, 64
	v_lshl_add_u64 v[176:177], v[6:7], 1, s[22:23]
	v_lshlrev_b32_e32 v6, 3, v3
	v_writelane_b32 v253, s12, 29
	v_lshlrev_b32_e32 v19, 4, v0
	v_lshlrev_b32_e32 v21, 4, v3
	v_lshlrev_b32_e32 v23, 4, v11
	v_ashrrev_i32_e32 v7, 31, v6
	v_mul_u32_u24_e32 v0, 0x150, v13
	v_lshl_add_u32 v25, v182, 3, 0
	v_mul_u32_u24_e32 v26, 0x88, v13
	v_writelane_b32 v253, s13, 30
	v_mov_b32_e32 v14, v1
	v_mov_b32_e32 v15, v1
	s_movk_i32 s12, 0x5400
	v_lshl_add_u64 v[178:179], v[6:7], 1, s[22:23]
	v_lshl_add_u64 v[180:181], v[4:5], 1, s[22:23]
	v_add_u32_e32 v157, 0x0, v201
	v_mul_u32_u24_e32 v158, 0xc31, v157
	v_lshrrev_b32_e32 v158, 16, v158
	v_mul_u32_u24_e32 v159, 21, v158
	v_sub_u32_e32 v159, v157, v159
	v_min_u32_e32 v159, 19, v159
	v_mul_u32_u24_e32 v158, 0x140, v158
	v_lshl_add_u32 v154, v159, 4, v158
	v_add_u32_e32 v157, 0x200, v201
	v_mul_u32_u24_e32 v158, 0xc31, v157
	v_lshrrev_b32_e32 v158, 16, v158
	v_mul_u32_u24_e32 v159, 21, v158
	v_sub_u32_e32 v159, v157, v159
	v_min_u32_e32 v159, 19, v159
	v_mul_u32_u24_e32 v158, 0x140, v158
	v_lshl_add_u32 v155, v159, 4, v158
	v_add_u32_e32 v157, 0x400, v201
	v_mul_u32_u24_e32 v158, 0xc31, v157
	v_lshrrev_b32_e32 v158, 16, v158
	v_mul_u32_u24_e32 v159, 21, v158
	v_sub_u32_e32 v159, v157, v159
	v_min_u32_e32 v159, 19, v159
	v_mul_u32_u24_e32 v158, 0x140, v158
	v_lshl_add_u32 v156, v159, 4, v158
	v_mov_b32_e32 v152, s22
	v_mov_b32_e32 v153, s23
	v_readfirstlane_b32 s99, v201
	s_nop 3
	s_lshr_b32 s99, s99, 6
	s_lshl_b32 s99, s99, 10
	s_mov_b32 s98, 0
	s_mov_b32 m0, s99
	s_nop 0
	global_load_lds_dwordx4 v154, s[22:23]
	s_add_i32 m0, s99, 0x2000
	s_nop 0
	global_load_lds_dwordx4 v155, s[22:23]
	s_cmp_ge_u32 s99, 0x1400
	s_cbranch_scc1 .Lkdma0_skip
	s_add_i32 m0, s99, 0x4000
	s_nop 0
	global_load_lds_dwordx4 v156, s[22:23]
.Lkdma0_skip:
	v_add3_u32 v188, 0, v0, v2
	v_mov_b32_e32 v0, v1
	v_mov_b32_e32 v2, v1
	v_mov_b32_e32 v3, v1
	v_mov_b32_e32 v4, v1
	v_mov_b32_e32 v5, v1
	v_mov_b32_e32 v6, v1
	v_mov_b32_e32 v7, v1
	v_mov_b32_e32 v8, v1
	v_mov_b32_e32 v9, v1
	v_mov_b32_e32 v10, v1
	v_mov_b32_e32 v11, v1
	v_mov_b32_e32 v12, v1
	v_mov_b32_e32 v13, v1
	v_add_u32_e32 v189, v18, v19
	v_add_u32_e32 v190, v20, v21
	v_add_u32_e32 v191, v22, v23
	s_waitcnt vmcnt(3)
	v_add3_u32 v192, v17, v24, s12
	v_add3_u32 v193, v17, v16, s12
	v_add_u32_e32 v194, v25, v26
	v_mov_b64_e32 v[30:31], v[14:15]
	v_mov_b64_e32 v[46:47], v[14:15]
	v_mov_b64_e32 v[62:63], v[14:15]
	v_mov_b64_e32 v[78:79], v[14:15]
	s_sub_i32 s57, 64, s33
	s_mov_b32 s58, 0
	v_mov_b32_e32 v195, 0xf149f2ca
	v_mov_b32_e32 v184, 0
	v_mov_b64_e32 v[28:29], v[12:13]
	v_mov_b64_e32 v[26:27], v[10:11]
	v_mov_b64_e32 v[24:25], v[8:9]
	v_mov_b64_e32 v[22:23], v[6:7]
	v_mov_b64_e32 v[20:21], v[4:5]
	v_mov_b64_e32 v[18:19], v[2:3]
	v_mov_b64_e32 v[16:17], v[0:1]
	v_mov_b64_e32 v[44:45], v[12:13]
	v_mov_b64_e32 v[42:43], v[10:11]
	v_mov_b64_e32 v[40:41], v[8:9]
	v_mov_b64_e32 v[38:39], v[6:7]
	v_mov_b64_e32 v[36:37], v[4:5]
	v_mov_b64_e32 v[34:35], v[2:3]
	v_mov_b64_e32 v[32:33], v[0:1]
	v_mov_b64_e32 v[60:61], v[12:13]
	v_mov_b64_e32 v[58:59], v[10:11]
	v_mov_b64_e32 v[56:57], v[8:9]
	v_mov_b64_e32 v[54:55], v[6:7]
	v_mov_b64_e32 v[52:53], v[4:5]
	v_mov_b64_e32 v[50:51], v[2:3]
	v_mov_b64_e32 v[48:49], v[0:1]
	v_mov_b64_e32 v[76:77], v[12:13]
	v_mov_b64_e32 v[74:75], v[10:11]
	v_mov_b64_e32 v[72:73], v[8:9]
	v_mov_b64_e32 v[70:71], v[6:7]
	v_mov_b64_e32 v[68:69], v[4:5]
	v_mov_b64_e32 v[66:67], v[2:3]
	v_mov_b64_e32 v[64:65], v[0:1]
	s_branch .LBB0_556
.LBB0_555:
	s_or_b64 exec, exec, s[22:23]
	s_xor_b32 s98, s98, 0x10000
	v_xor_b32_e32 v188, 0x10000, v188
	v_xor_b32_e32 v189, 0x10000, v189
	v_xor_b32_e32 v190, 0x10000, v190
	v_xor_b32_e32 v191, 0x10000, v191
	v_xor_b32_e32 v192, 0x10000, v192
	v_xor_b32_e32 v193, 0x10000, v193
	v_xor_b32_e32 v194, 0x10000, v194
	v_readlane_b32 s12, v253, 29
	v_readlane_b32 s13, v253, 30
	s_add_i32 s12, s12, 64
	s_add_i32 s58, s58, 1
	v_writelane_b32 v253, s12, 29
	s_cmp_eq_u32 s57, s58
	s_nop 0
	v_writelane_b32 v253, s13, 30
	s_cbranch_scc1 .LBB0_573
.LBB0_556:
	s_cmp_ge_u32 s58, s27
	s_waitcnt vmcnt(0)
	ds_write2_b64 v192, v[168:169], v[170:171] offset1:1
	ds_write2_b64 v193, v[164:165], v[166:167] offset1:1
	s_waitcnt lgkmcnt(0)
	s_barrier
	s_cbranch_scc1 .LBB0_566
	v_readfirstlane_b32 s12, v152
	v_readfirstlane_b32 s13, v153
	v_readlane_b32 s22, v253, 29
	s_nop 3
	s_mul_i32 s23, s22, 0x140
	s_add_u32 s12, s12, s23
	s_addc_u32 s13, s13, 0
	s_xor_b32 s23, s98, 0x10000
	s_add_i32 s23, s23, s99
	s_mov_b32 m0, s23
	s_nop 0
	global_load_lds_dwordx4 v154, s[12:13]
	s_add_i32 m0, s23, 0x2000
	s_nop 0
	global_load_lds_dwordx4 v155, s[12:13]
	s_cmp_ge_u32 s99, 0x1400
	s_cbranch_scc1 .Lkdma_skip
	s_add_i32 m0, s23, 0x4000
	s_nop 0
	global_load_lds_dwordx4 v156, s[12:13]
.Lkdma_skip:
	v_readlane_b32 s12, v253, 29
	v_readlane_b32 s13, v253, 30
	s_lshl_b64 s[12:13], s[12:13], 1
	s_nop 0
	v_lshl_add_u64 v[2:3], v[172:173], 0, s[12:13]
	v_lshl_add_u64 v[4:5], v[174:175], 0, s[12:13]
	global_load_dwordx4 v[168:171], v[2:3], off
	global_load_dwordx4 v[164:167], v[4:5], off
.LBB0_566:
	s_and_saveexec_b64 s[22:23], vcc
	s_cbranch_execz .LBB0_555
	ds_read_b128 v[196:199], v188
	ds_read_b128 v[202:205], v188 offset:32
	ds_read_b128 v[206:209], v188 offset:64
	ds_read_b128 v[210:213], v188 offset:96
	ds_read_b128 v[220:223], v188 offset:128
	ds_read_b128 v[224:227], v188 offset:160
	ds_read_b128 v[2:5], v188 offset:192
	ds_read_b128 v[6:9], v188 offset:224
	s_waitcnt lgkmcnt(7)
	v_mfma_f32_32x32x16_bf16 v[96:111], v[196:199], v[148:151], 0
	ds_read_b128 v[196:199], v188 offset:256
	s_waitcnt lgkmcnt(7)
	v_mfma_f32_32x32x16_bf16 v[96:111], v[202:205], v[144:147], v[96:111]
	ds_read_b128 v[202:205], v188 offset:288
	s_waitcnt lgkmcnt(7)
	v_mfma_f32_32x32x16_bf16 v[96:111], v[206:209], v[140:143], v[96:111]
	ds_read_b128 v[206:209], v188 offset:10752
	s_waitcnt lgkmcnt(7)
	v_mfma_f32_32x32x16_bf16 v[96:111], v[210:213], v[136:139], v[96:111]
	ds_read_b128 v[210:213], v188 offset:10784
	s_waitcnt lgkmcnt(7)
	v_mfma_f32_32x32x16_bf16 v[96:111], v[220:223], v[132:135], v[96:111]
	ds_read_b128 v[220:223], v188 offset:10816
	s_waitcnt lgkmcnt(7)
	v_mfma_f32_32x32x16_bf16 v[96:111], v[224:227], v[128:131], v[96:111]
	ds_read_b128 v[224:227], v188 offset:10848
	s_waitcnt lgkmcnt(7)
	v_mfma_f32_32x32x16_bf16 v[96:111], v[2:5], v[124:127], v[96:111]
	ds_read_b128 v[2:5], v188 offset:10880
	s_waitcnt lgkmcnt(7)
	v_mfma_f32_32x32x16_bf16 v[96:111], v[6:9], v[120:123], v[96:111]
	ds_read_b128 v[6:9], v188 offset:10912
	s_waitcnt lgkmcnt(7)
	v_mfma_f32_32x32x16_bf16 v[96:111], v[196:199], v[116:119], v[96:111]
	ds_read_b128 v[196:199], v188 offset:10944
	s_waitcnt lgkmcnt(7)
	v_mfma_f32_32x32x16_bf16 v[96:111], v[202:205], v[112:115], v[96:111]
	ds_read_b128 v[202:205], v188 offset:10976
	s_waitcnt lgkmcnt(7)
	v_mfma_f32_32x32x16_bf16 v[80:95], v[206:209], v[148:151], 0
	ds_read_b128 v[206:209], v188 offset:11008
	s_waitcnt lgkmcnt(7)
	v_mfma_f32_32x32x16_bf16 v[80:95], v[210:213], v[144:147], v[80:95]
	ds_read_b128 v[210:213], v188 offset:11040
	s_waitcnt lgkmcnt(7)
	v_mfma_f32_32x32x16_bf16 v[80:95], v[220:223], v[140:143], v[80:95]
	s_waitcnt lgkmcnt(6)
	v_mfma_f32_32x32x16_bf16 v[80:95], v[224:227], v[136:139], v[80:95]
	s_waitcnt lgkmcnt(5)
	v_mfma_f32_32x32x16_bf16 v[80:95], v[2:5], v[132:135], v[80:95]
	s_waitcnt lgkmcnt(4)
	v_mfma_f32_32x32x16_bf16 v[80:95], v[6:9], v[128:131], v[80:95]
	s_waitcnt lgkmcnt(3)
	v_mfma_f32_32x32x16_bf16 v[80:95], v[196:199], v[124:127], v[80:95]
	v_max_f32_e32 v0, v97, v97
	v_max_f32_e32 v10, v96, v96
	v_max_f32_e32 v0, v10, v0
	v_max3_f32 v0, v0, v98, v99
	v_max3_f32 v0, v0, v100, v101
	v_max3_f32 v0, v0, v102, v103
	v_max3_f32 v0, v0, v104, v105
	v_max3_f32 v0, v0, v106, v107
	v_max3_f32 v0, v0, v108, v109
	v_max3_f32 v0, v0, v110, v111
	v_and_b32_e32 v3, 64, v218
	v_xor_b32_e32 v2, 32, v218
	v_add_u32_e32 v3, 64, v3
	v_cmp_lt_i32_e64 s[12:13], v2, v3
	s_nop 1
	v_cndmask_b32_e64 v2, v218, v2, s[12:13]
	s_waitcnt lgkmcnt(2)
	v_mfma_f32_32x32x16_bf16 v[80:95], v[202:205], v[120:123], v[80:95]
	s_waitcnt lgkmcnt(1)
	v_mfma_f32_32x32x16_bf16 v[80:95], v[206:209], v[116:119], v[80:95]
	s_waitcnt lgkmcnt(0)
	v_mfma_f32_32x32x16_bf16 v[80:95], v[210:213], v[112:115], v[80:95]
	v_lshlrev_b32_e32 v2, 2, v2
	s_nop 10
	v_max3_f32 v0, v0, v80, v81
	v_max3_f32 v0, v0, v82, v83
	v_max3_f32 v0, v0, v84, v85
	v_max3_f32 v0, v0, v86, v87
	v_max3_f32 v0, v0, v88, v89
	v_max3_f32 v0, v0, v90, v91
	v_max3_f32 v0, v0, v92, v93
	v_max3_f32 v0, v0, v94, v95
	ds_bpermute_b32 v2, v2, v0
	s_waitcnt lgkmcnt(0)
	v_add_u32_e32 v224, 0x5000, v194
	v_add_u32_e32 v225, 0x6000, v194
	v_add_u32_e32 v226, 0x7000, v194
	v_add_u32_e32 v227, 0x8000, v194
	ds_read2_b64 v[196:199], v224 offset0:128 offset1:130
	ds_read2_b64 v[202:205], v225 offset0:160 offset1:162
	ds_read2_b64 v[206:209], v226 offset0:192 offset1:194
	ds_read2_b64 v[210:213], v227 offset0:224 offset1:226
	ds_read2_b64 v[220:223], v224 offset0:132 offset1:134
	v_max3_f32 v0, v195, v0, v2
	v_sub_f32 v4, v97, v0
	v_sub_f32 v3, v96, v0
	v_sub_f32 v5, v100, v0
	v_sub_f32_e32 v2, v195, v0
	v_exp_f32_e32 v8, v4
	v_sub_f32 v4, v98, v0
	v_exp_f32_e32 v3, v3
	v_exp_f32_e32 v9, v4
	v_sub_f32 v4, v99, v0
	v_exp_f32_e32 v11, v5
	v_exp_f32_e32 v10, v4
	v_add_f32 v4, v1, v3
	v_sub_f32 v5, v101, v0
	v_exp_f32_e32 v2, v2
	v_add_f32 v4, v4, v8
	v_exp_f32_e32 v12, v5
	v_add_f32 v4, v4, v9
	v_sub_f32 v5, v102, v0
	v_cvt_pk_bf16_f32 v8, v3, v8
	v_add_f32 v4, v4, v10
	v_exp_f32_e32 v13, v5
	v_add_f32 v4, v4, v11
	v_sub_f32 v5, v103, v0
	v_add_f32 v4, v4, v12
	v_exp_f32_e32 v14, v5
	v_add_f32 v4, v4, v13
	v_cvt_pk_bf16_f32 v9, v9, v10
	v_add_f32 v96, v4, v14
	v_sub_f32 v4, v104, v0
	v_exp_f32_e32 v97, v4
	v_sub_f32 v4, v105, v0
	v_cvt_pk_bf16_f32 v10, v11, v12
	v_exp_f32_e32 v98, v4
	v_sub_f32 v4, v106, v0
	v_cvt_pk_bf16_f32 v11, v13, v14
	v_exp_f32_e32 v99, v4
	v_sub_f32 v4, v107, v0
	v_exp_f32_e32 v100, v4
	v_sub_f32 v4, v108, v0
	v_pk_mul_f32 v[64:65], v[64:65], v[2:3] op_sel_hi:[1,0]
	v_pk_mul_f32 v[66:67], v[66:67], v[2:3] op_sel_hi:[1,0]
	v_pk_mul_f32 v[68:69], v[68:69], v[2:3] op_sel_hi:[1,0]
	s_nop 0
	v_exp_f32_e32 v101, v4
	v_sub_f32 v4, v109, v0
	v_pk_mul_f32 v[70:71], v[70:71], v[2:3] op_sel_hi:[1,0]
	v_pk_mul_f32 v[72:73], v[72:73], v[2:3] op_sel_hi:[1,0]
	s_nop 0
	v_exp_f32_e32 v102, v4
	v_sub_f32 v4, v110, v0
	v_pk_mul_f32 v[74:75], v[74:75], v[2:3] op_sel_hi:[1,0]
	v_pk_mul_f32 v[76:77], v[76:77], v[2:3] op_sel_hi:[1,0]
	v_pk_mul_f32 v[78:79], v[78:79], v[2:3] op_sel_hi:[1,0]
	s_nop 0
	v_exp_f32_e32 v103, v4
	s_waitcnt lgkmcnt(4)
	v_mfma_f32_32x32x16_bf16 v[64:79], v[196:199], v[8:11], v[64:79]
	ds_read2_b64 v[196:199], v225 offset0:164 offset1:166
	v_pk_mul_f32 v[48:49], v[48:49], v[2:3] op_sel_hi:[1,0]
	v_pk_mul_f32 v[50:51], v[50:51], v[2:3] op_sel_hi:[1,0]
	v_pk_mul_f32 v[52:53], v[52:53], v[2:3] op_sel_hi:[1,0]
	v_pk_mul_f32 v[54:55], v[54:55], v[2:3] op_sel_hi:[1,0]
	v_pk_mul_f32 v[56:57], v[56:57], v[2:3] op_sel_hi:[1,0]
	v_pk_mul_f32 v[58:59], v[58:59], v[2:3] op_sel_hi:[1,0]
	v_pk_mul_f32 v[60:61], v[60:61], v[2:3] op_sel_hi:[1,0]
	v_pk_mul_f32 v[62:63], v[62:63], v[2:3] op_sel_hi:[1,0]
	s_waitcnt lgkmcnt(4)
	v_mfma_f32_32x32x16_bf16 v[48:63], v[202:205], v[8:11], v[48:63]
	ds_read2_b64 v[202:205], v226 offset0:196 offset1:198
	v_pk_mul_f32 v[32:33], v[32:33], v[2:3] op_sel_hi:[1,0]
	v_pk_mul_f32 v[34:35], v[34:35], v[2:3] op_sel_hi:[1,0]
	v_pk_mul_f32 v[36:37], v[36:37], v[2:3] op_sel_hi:[1,0]
	v_pk_mul_f32 v[38:39], v[38:39], v[2:3] op_sel_hi:[1,0]
	v_pk_mul_f32 v[40:41], v[40:41], v[2:3] op_sel_hi:[1,0]
	v_pk_mul_f32 v[42:43], v[42:43], v[2:3] op_sel_hi:[1,0]
	v_pk_mul_f32 v[44:45], v[44:45], v[2:3] op_sel_hi:[1,0]
	v_pk_mul_f32 v[46:47], v[46:47], v[2:3] op_sel_hi:[1,0]
	v_pk_mul_f32 v[16:17], v[16:17], v[2:3] op_sel_hi:[1,0]
	v_pk_mul_f32 v[18:19], v[18:19], v[2:3] op_sel_hi:[1,0]
	v_pk_mul_f32 v[20:21], v[20:21], v[2:3] op_sel_hi:[1,0]
	s_waitcnt lgkmcnt(4)
	v_mfma_f32_32x32x16_bf16 v[32:47], v[206:209], v[8:11], v[32:47]
	ds_read2_b64 v[206:209], v227 offset0:228 offset1:230
	v_pk_mul_f32 v[22:23], v[22:23], v[2:3] op_sel_hi:[1,0]
	v_pk_mul_f32 v[24:25], v[24:25], v[2:3] op_sel_hi:[1,0]
	v_pk_mul_f32 v[26:27], v[26:27], v[2:3] op_sel_hi:[1,0]
	v_pk_mul_f32 v[28:29], v[28:29], v[2:3] op_sel_hi:[1,0]
	v_pk_mul_f32 v[30:31], v[30:31], v[2:3] op_sel_hi:[1,0]
	v_mov_b32_e32 v195, v0
	s_waitcnt lgkmcnt(4)
	v_mfma_f32_32x32x16_bf16 v[16:31], v[210:213], v[8:11], v[16:31]
	ds_read2_b64 v[210:213], v224 offset0:136 offset1:138
	v_sub_f32 v8, v111, v0
	v_cvt_pk_bf16_f32 v9, v99, v100
	v_exp_f32_e32 v107, v8
	v_cvt_pk_bf16_f32 v8, v97, v98
	v_cvt_pk_bf16_f32 v10, v101, v102
	v_cvt_pk_bf16_f32 v11, v103, v107
	s_nop 0
	s_waitcnt lgkmcnt(4)
	v_mfma_f32_32x32x16_bf16 v[64:79], v[220:223], v[8:11], v[64:79]
	ds_read2_b64 v[220:223], v225 offset0:168 offset1:170
	v_add_f32 v4, v96, v97
	s_nop 0
	v_add_f32 v4, v4, v98
	s_nop 0
	v_add_f32 v4, v4, v99
	s_nop 0
	v_add_f32 v96, v4, v100
	v_sub_f32 v4, v80, v0
	s_waitcnt lgkmcnt(4)
	v_mfma_f32_32x32x16_bf16 v[48:63], v[196:199], v[8:11], v[48:63]
	ds_read2_b64 v[196:199], v226 offset0:200 offset1:202
	v_exp_f32_e32 v80, v4
	v_sub_f32 v12, v81, v0
	s_nop 0
	v_exp_f32_e32 v81, v12
	v_sub_f32 v12, v82, v0
	s_nop 0
	v_exp_f32_e32 v82, v12
	v_sub_f32 v12, v83, v0
	s_waitcnt lgkmcnt(4)
	v_mfma_f32_32x32x16_bf16 v[32:47], v[202:205], v[8:11], v[32:47]
	ds_read2_b64 v[202:205], v227 offset0:232 offset1:234
	v_exp_f32_e32 v83, v12
	v_sub_f32 v4, v84, v0
	s_nop 0
	v_exp_f32_e32 v84, v4
	v_sub_f32 v4, v85, v0
	s_nop 0
	v_exp_f32_e32 v85, v4
	v_sub_f32 v4, v86, v0
	s_waitcnt lgkmcnt(4)
	v_mfma_f32_32x32x16_bf16 v[16:31], v[206:209], v[8:11], v[16:31]
	ds_read2_b64 v[206:209], v224 offset0:140 offset1:142
	v_exp_f32_e32 v86, v4
	v_sub_f32 v8, v87, v0
	v_exp_f32_e32 v87, v8
	v_cvt_pk_bf16_f32 v8, v80, v81
	v_cvt_pk_bf16_f32 v9, v82, v83
	v_cvt_pk_bf16_f32 v10, v84, v85
	v_cvt_pk_bf16_f32 v11, v86, v87
	s_nop 0
	s_waitcnt lgkmcnt(4)
	v_mfma_f32_32x32x16_bf16 v[64:79], v[210:213], v[8:11], v[64:79]
	ds_read2_b64 v[210:213], v225 offset0:172 offset1:174
	v_add_f32 v4, v96, v101
	s_nop 0
	v_add_f32 v4, v4, v102
	s_nop 0
	v_add_f32 v4, v4, v103
	s_nop 0
	v_add_f32 v96, v4, v107
	v_sub_f32 v4, v88, v0
	s_waitcnt lgkmcnt(4)
	v_mfma_f32_32x32x16_bf16 v[48:63], v[220:223], v[8:11], v[48:63]
	ds_read2_b64 v[220:223], v226 offset0:204 offset1:206
	v_exp_f32_e32 v88, v4
	v_sub_f32 v12, v89, v0
	s_nop 0
	v_exp_f32_e32 v89, v12
	v_sub_f32 v12, v90, v0
	s_nop 0
	v_exp_f32_e32 v90, v12
	v_sub_f32 v12, v91, v0
	s_waitcnt lgkmcnt(4)
	v_mfma_f32_32x32x16_bf16 v[32:47], v[196:199], v[8:11], v[32:47]
	ds_read2_b64 v[196:199], v227 offset0:236 offset1:238
	v_exp_f32_e32 v91, v12
	v_sub_f32 v4, v92, v0
	s_nop 0
	v_exp_f32_e32 v92, v4
	v_sub_f32 v4, v93, v0
	s_nop 0
	v_exp_f32_e32 v93, v4
	v_sub_f32 v4, v94, v0
	s_waitcnt lgkmcnt(4)
	v_mfma_f32_32x32x16_bf16 v[16:31], v[202:205], v[8:11], v[16:31]
	v_exp_f32_e32 v94, v4
	v_sub_f32 v8, v95, v0
	v_cvt_pk_bf16_f32 v9, v90, v91
	v_exp_f32_e32 v95, v8
	v_cvt_pk_bf16_f32 v8, v88, v89
	v_cvt_pk_bf16_f32 v10, v92, v93
	v_add_f32 v3, v96, v80
	v_cvt_pk_bf16_f32 v11, v94, v95
	v_add_f32 v3, v3, v81
	s_nop 0
	v_add_f32 v3, v3, v82
	s_waitcnt lgkmcnt(3)
	v_mfma_f32_32x32x16_bf16 v[64:79], v[206:209], v[8:11], v[64:79]
	v_add_f32 v3, v3, v83
	s_nop 0
	v_add_f32 v3, v3, v84
	s_nop 0
	v_add_f32 v3, v3, v85
	s_waitcnt lgkmcnt(2)
	v_mfma_f32_32x32x16_bf16 v[48:63], v[210:213], v[8:11], v[48:63]
	v_add_f32 v3, v3, v86
	s_nop 0
	v_add_f32 v3, v3, v87
	s_nop 0
	v_add_f32 v3, v3, v88
	s_nop 0
	v_add_f32 v3, v3, v89
	s_waitcnt lgkmcnt(1)
	v_mfma_f32_32x32x16_bf16 v[32:47], v[220:223], v[8:11], v[32:47]
	v_add_f32 v3, v3, v90
	s_nop 0
	v_add_f32 v3, v3, v91
	s_nop 0
	v_add_f32 v3, v3, v92
	s_nop 0
	v_add_f32 v3, v3, v93
	s_waitcnt lgkmcnt(0)
	v_mfma_f32_32x32x16_bf16 v[16:31], v[196:199], v[8:11], v[16:31]
	v_add_f32 v3, v3, v94
	s_nop 0
	v_add_f32 v3, v3, v95
	s_nop 0
	v_fmac_f32_e32 v3, v184, v2
	v_mov_b32_e32 v184, v3
	s_branch .LBB0_555
.LBB0_572:
	s_mov_b64 s[22:23], 0
	s_cbranch_execnz .LBB0_576
	s_branch .LBB0_607
